# attention epilogue: 16 serialized subln loads hoisted into one batch, counted vmcnt so output stores stream
# speedup vs baseline: 1.0064x; 1.0064x over previous
.LBB0_222:
	s_or_b64 exec, exec, s[6:7]
	s_waitcnt lgkmcnt(0)
	s_barrier
	s_and_saveexec_b64 s[6:7], s[40:41]
	s_cbranch_execz .LBB0_195
	global_load_dwordx4 v[148:151], v[184:185], off
	global_load_dwordx4 v[152:155], v[184:185], off offset:32
	global_load_dwordx4 v[156:159], v[184:185], off offset:64
	global_load_dwordx4 v[162:165], v[184:185], off offset:96
	global_load_dwordx4 v[222:225], v[184:185], off offset:128
	global_load_dwordx4 v[236:239], v[184:185], off offset:160
	global_load_dwordx4 v[240:243], v[184:185], off offset:192
	global_load_dwordx4 v[244:247], v[184:185], off offset:224
	global_load_dwordx4 v[248:251], v[184:185], off offset:256
	global_load_dwordx4 v[230:233], v[184:185], off offset:288
	ds_read2st64_b32 v[78:79], v206 offset1:1
	ds_read2st64_b32 v[82:83], v206 offset0:2 offset1:3
	ds_read2st64_b32 v[96:97], v206 offset0:4 offset1:5
	ds_read2st64_b32 v[86:87], v206 offset0:6 offset1:7
	ds_read2st64_b32 v[100:101], v206 offset0:8 offset1:9
	ds_read2st64_b32 v[118:119], v206 offset0:10 offset1:11
	ds_read2st64_b32 v[120:121], v206 offset0:12 offset1:13
	ds_read2st64_b32 v[122:123], v206 offset0:14 offset1:15
	ds_read2st64_b32 v[124:125], v206 offset0:16 offset1:17
	ds_read2st64_b32 v[126:127], v206 offset0:18 offset1:19
	ds_read2st64_b32 v[128:129], v206 offset0:20 offset1:21
	ds_read2st64_b32 v[130:131], v206 offset0:22 offset1:23
	ds_read2st64_b32 v[132:133], v206 offset0:24 offset1:25
	ds_read2st64_b32 v[134:135], v206 offset0:26 offset1:27
	ds_read2st64_b32 v[114:115], v206 offset0:28 offset1:29
	ds_read2st64_b32 v[136:137], v206 offset0:30 offset1:31
	ds_read2st64_b32 v[110:111], v206 offset0:32 offset1:33
	ds_read2st64_b32 v[116:117], v206 offset0:34 offset1:35
	ds_read2st64_b32 v[106:107], v206 offset0:36 offset1:37
	ds_read2st64_b32 v[112:113], v206 offset0:38 offset1:39
	ds_read2st64_b32 v[102:103], v206 offset0:40 offset1:41
	ds_read2st64_b32 v[108:109], v206 offset0:42 offset1:43
	ds_read2st64_b32 v[98:99], v206 offset0:44 offset1:45
	ds_read2st64_b32 v[104:105], v206 offset0:46 offset1:47
	ds_read2st64_b32 v[90:91], v206 offset0:48 offset1:49
	ds_read2st64_b32 v[94:95], v206 offset0:50 offset1:51
	ds_read2st64_b32 v[76:77], v206 offset0:52 offset1:53
	ds_read2st64_b32 v[84:85], v206 offset0:54 offset1:55
	ds_read2st64_b32 v[74:75], v206 offset0:56 offset1:57
	ds_read2st64_b32 v[80:81], v206 offset0:58 offset1:59
	ds_read2st64_b32 v[64:65], v206 offset0:60 offset1:61
	s_waitcnt lgkmcnt(14)
	v_pk_mul_f32 v[82:83], v[186:187], v[82:83]
	s_lshl_b32 s4, s27, 1
	v_pk_fma_f32 v[82:83], v[50:51], v[70:71], v[82:83] op_sel_hi:[1,0,1] neg_lo:[0,0,1] neg_hi:[0,0,1]
	v_pk_mul_f32 v[50:51], v[186:187], v[78:79]
	s_waitcnt lgkmcnt(0)
	v_pk_mul_f32 v[64:65], v[186:187], v[64:65]
	v_pk_fma_f32 v[92:93], v[48:49], v[70:71], v[50:51] op_sel_hi:[1,0,1] neg_lo:[0,0,1] neg_hi:[0,0,1]
	v_pk_mul_f32 v[48:49], v[186:187], v[86:87]
	v_pk_fma_f32 v[64:65], v[12:13], v[70:71], v[64:65] op_sel_hi:[1,0,1] neg_lo:[0,0,1] neg_hi:[0,0,1]
	v_pk_fma_f32 v[86:87], v[54:55], v[70:71], v[48:49] op_sel_hi:[1,0,1] neg_lo:[0,0,1] neg_hi:[0,0,1]
	v_pk_mul_f32 v[48:49], v[186:187], v[96:97]
	ds_read_b32 v12, v206 offset:15872
	ds_read_b32 v13, v210
	v_pk_fma_f32 v[96:97], v[52:53], v[70:71], v[48:49] op_sel_hi:[1,0,1] neg_lo:[0,0,1] neg_hi:[0,0,1]
	v_pk_mul_f32 v[48:49], v[186:187], v[118:119]
	v_pk_mul_f32 v[140:141], v[92:93], v[92:93]
	v_pk_fma_f32 v[78:79], v[58:59], v[70:71], v[48:49] op_sel_hi:[1,0,1] neg_lo:[0,0,1] neg_hi:[0,0,1]
	v_pk_mul_f32 v[48:49], v[186:187], v[100:101]
	s_waitcnt lgkmcnt(0)
	v_pk_mul_f32 v[12:13], v[186:187], v[12:13]
	v_pk_fma_f32 v[100:101], v[56:57], v[70:71], v[48:49] op_sel_hi:[1,0,1] neg_lo:[0,0,1] neg_hi:[0,0,1]
	v_pk_mul_f32 v[48:49], v[186:187], v[122:123]
	v_pk_fma_f32 v[68:69], v[14:15], v[70:71], v[12:13] op_sel_hi:[1,0,1] neg_lo:[0,0,1] neg_hi:[0,0,1]
	v_pk_fma_f32 v[56:57], v[62:63], v[70:71], v[48:49] op_sel_hi:[1,0,1] neg_lo:[0,0,1] neg_hi:[0,0,1]
	v_pk_mul_f32 v[48:49], v[186:187], v[120:121]
	v_lshl_add_u64 v[12:13], s[20:21], 0, v[160:161]
	v_pk_fma_f32 v[60:61], v[60:61], v[70:71], v[48:49] op_sel_hi:[1,0,1] neg_lo:[0,0,1] neg_hi:[0,0,1]
	v_pk_mul_f32 v[48:49], v[186:187], v[126:127]
	v_lshl_add_u64 v[12:13], v[12:13], 0, s[4:5]
	v_pk_fma_f32 v[52:53], v[34:35], v[70:71], v[48:49] op_sel_hi:[1,0,1] neg_lo:[0,0,1] neg_hi:[0,0,1]
	v_pk_mul_f32 v[34:35], v[186:187], v[124:125]
	v_lshlrev_b32_e32 v160, 1, v180
	v_pk_fma_f32 v[58:59], v[32:33], v[70:71], v[34:35] op_sel_hi:[1,0,1] neg_lo:[0,0,1] neg_hi:[0,0,1]
	v_pk_mul_f32 v[32:33], v[186:187], v[130:131]
	v_lshl_add_u64 v[66:67], v[12:13], 0, v[160:161]
	v_pk_fma_f32 v[48:49], v[38:39], v[70:71], v[32:33] op_sel_hi:[1,0,1] neg_lo:[0,0,1] neg_hi:[0,0,1]
	v_pk_mul_f32 v[32:33], v[186:187], v[128:129]
	v_pk_fma_f32 v[54:55], v[36:37], v[70:71], v[32:33] op_sel_hi:[1,0,1] neg_lo:[0,0,1] neg_hi:[0,0,1]
	v_pk_mul_f32 v[32:33], v[186:187], v[134:135]
	v_pk_mul_f32 v[138:139], v[82:83], v[82:83]
	v_pk_fma_f32 v[42:43], v[42:43], v[70:71], v[32:33] op_sel_hi:[1,0,1] neg_lo:[0,0,1] neg_hi:[0,0,1]
	v_pk_mul_f32 v[32:33], v[186:187], v[132:133]
	v_pk_mul_f32 v[144:145], v[96:97], v[96:97]
	v_pk_fma_f32 v[50:51], v[40:41], v[70:71], v[32:33] op_sel_hi:[1,0,1] neg_lo:[0,0,1] neg_hi:[0,0,1]
	v_pk_mul_f32 v[32:33], v[186:187], v[136:137]
	v_pk_mul_f32 v[142:143], v[86:87], v[86:87]
	v_pk_fma_f32 v[38:39], v[46:47], v[70:71], v[32:33] op_sel_hi:[1,0,1] neg_lo:[0,0,1] neg_hi:[0,0,1]
	v_pk_mul_f32 v[32:33], v[186:187], v[114:115]
	v_pk_mul_f32 v[146:147], v[100:101], v[100:101]
	v_pk_fma_f32 v[44:45], v[44:45], v[70:71], v[32:33] op_sel_hi:[1,0,1] neg_lo:[0,0,1] neg_hi:[0,0,1]
	v_pk_mul_f32 v[32:33], v[186:187], v[116:117]
	v_pk_mul_f32 v[118:119], v[78:79], v[78:79]
	v_pk_fma_f32 v[34:35], v[18:19], v[70:71], v[32:33] op_sel_hi:[1,0,1] neg_lo:[0,0,1] neg_hi:[0,0,1]
	v_pk_mul_f32 v[18:19], v[186:187], v[110:111]
	v_pk_mul_f32 v[120:121], v[60:61], v[60:61]
	v_pk_fma_f32 v[40:41], v[16:17], v[70:71], v[18:19] op_sel_hi:[1,0,1] neg_lo:[0,0,1] neg_hi:[0,0,1]
	v_pk_mul_f32 v[16:17], v[186:187], v[112:113]
	v_pk_mul_f32 v[62:63], v[56:57], v[56:57]
	v_pk_fma_f32 v[32:33], v[22:23], v[70:71], v[16:17] op_sel_hi:[1,0,1] neg_lo:[0,0,1] neg_hi:[0,0,1]
	v_pk_mul_f32 v[16:17], v[186:187], v[106:107]
	v_pk_mul_f32 v[124:125], v[58:59], v[58:59]
	v_pk_fma_f32 v[36:37], v[20:21], v[70:71], v[16:17] op_sel_hi:[1,0,1] neg_lo:[0,0,1] neg_hi:[0,0,1]
	v_pk_mul_f32 v[16:17], v[186:187], v[108:109]
	v_pk_mul_f32 v[122:123], v[52:53], v[52:53]
	v_pk_fma_f32 v[22:23], v[26:27], v[70:71], v[16:17] op_sel_hi:[1,0,1] neg_lo:[0,0,1] neg_hi:[0,0,1]
	v_pk_mul_f32 v[16:17], v[186:187], v[102:103]
	v_pk_mul_f32 v[128:129], v[54:55], v[54:55]
	v_pk_fma_f32 v[26:27], v[24:25], v[70:71], v[16:17] op_sel_hi:[1,0,1] neg_lo:[0,0,1] neg_hi:[0,0,1]
	v_pk_mul_f32 v[16:17], v[186:187], v[104:105]
	v_pk_mul_f32 v[126:127], v[48:49], v[48:49]
	v_pk_fma_f32 v[18:19], v[30:31], v[70:71], v[16:17] op_sel_hi:[1,0,1] neg_lo:[0,0,1] neg_hi:[0,0,1]
	v_pk_mul_f32 v[16:17], v[186:187], v[98:99]
	v_pk_mul_f32 v[132:133], v[50:51], v[50:51]
	v_pk_fma_f32 v[24:25], v[28:29], v[70:71], v[16:17] op_sel_hi:[1,0,1] neg_lo:[0,0,1] neg_hi:[0,0,1]
	v_pk_mul_f32 v[16:17], v[186:187], v[94:95]
	v_pk_mul_f32 v[130:131], v[42:43], v[42:43]
	v_pk_fma_f32 v[16:17], v[2:3], v[70:71], v[16:17] op_sel_hi:[1,0,1] neg_lo:[0,0,1] neg_hi:[0,0,1]
	v_pk_mul_f32 v[2:3], v[186:187], v[90:91]
	v_pk_mul_f32 v[114:115], v[44:45], v[44:45]
	v_pk_fma_f32 v[20:21], v[0:1], v[70:71], v[2:3] op_sel_hi:[1,0,1] neg_lo:[0,0,1] neg_hi:[0,0,1]
	v_pk_mul_f32 v[0:1], v[186:187], v[84:85]
	v_pk_mul_f32 v[46:47], v[38:39], v[38:39]
	v_pk_fma_f32 v[2:3], v[6:7], v[70:71], v[0:1] op_sel_hi:[1,0,1] neg_lo:[0,0,1] neg_hi:[0,0,1]
	v_pk_mul_f32 v[0:1], v[186:187], v[76:77]
	v_pk_mul_f32 v[110:111], v[40:41], v[40:41]
	v_pk_fma_f32 v[6:7], v[4:5], v[70:71], v[0:1] op_sel_hi:[1,0,1] neg_lo:[0,0,1] neg_hi:[0,0,1]
	v_pk_mul_f32 v[0:1], v[186:187], v[80:81]
	v_pk_mul_f32 v[4:5], v[186:187], v[74:75]
	v_pk_fma_f32 v[0:1], v[10:11], v[70:71], v[0:1] op_sel_hi:[1,0,1] neg_lo:[0,0,1] neg_hi:[0,0,1]
	v_pk_fma_f32 v[4:5], v[8:9], v[70:71], v[4:5] op_sel_hi:[1,0,1] neg_lo:[0,0,1] neg_hi:[0,0,1]
	v_add_f32_e32 v70, v140, v141
	v_add_f32_e32 v70, v70, v138
	v_add_f32_e32 v70, v70, v139
	v_add_f32_e32 v70, v70, v144
	v_add_f32_e32 v70, v70, v145
	v_add_f32_e32 v70, v70, v142
	v_add_f32_e32 v70, v70, v143
	v_add_f32_e32 v70, v70, v146
	v_add_f32_e32 v70, v70, v147
	v_add_f32_e32 v70, v70, v118
	v_add_f32_e32 v70, v70, v119
	v_add_f32_e32 v70, v70, v120
	v_add_f32_e32 v70, v70, v121
	v_add_f32_e32 v62, v70, v62
	v_add_f32_e32 v62, v62, v63
	v_add_f32_e32 v62, v62, v124
	v_add_f32_e32 v62, v62, v125
	v_add_f32_e32 v62, v62, v122
	v_add_f32_e32 v62, v62, v123
	v_add_f32_e32 v62, v62, v128
	v_add_f32_e32 v62, v62, v129
	v_add_f32_e32 v62, v62, v126
	v_add_f32_e32 v62, v62, v127
	v_add_f32_e32 v62, v62, v132
	v_add_f32_e32 v62, v62, v133
	v_add_f32_e32 v62, v62, v130
	v_add_f32_e32 v62, v62, v131
	v_add_f32_e32 v62, v62, v114
	v_add_f32_e32 v62, v62, v115
	v_add_f32_e32 v46, v62, v46
	v_add_f32_e32 v46, v46, v47
	v_add_f32_e32 v46, v46, v110
	v_pk_mul_f32 v[116:117], v[34:35], v[34:35]
	v_add_f32_e32 v46, v46, v111
	v_add_f32_e32 v46, v46, v116
	v_pk_mul_f32 v[106:107], v[36:37], v[36:37]
	v_add_f32_e32 v46, v46, v117
	v_add_f32_e32 v46, v46, v106
	v_pk_mul_f32 v[112:113], v[32:33], v[32:33]
	v_add_f32_e32 v46, v46, v107
	v_add_f32_e32 v46, v46, v112
	v_pk_mul_f32 v[102:103], v[26:27], v[26:27]
	v_add_f32_e32 v46, v46, v113
	v_add_f32_e32 v46, v46, v102
	v_pk_mul_f32 v[108:109], v[22:23], v[22:23]
	v_add_f32_e32 v46, v46, v103
	v_add_f32_e32 v46, v46, v108
	v_pk_mul_f32 v[28:29], v[24:25], v[24:25]
	v_add_f32_e32 v46, v46, v109
	v_add_f32_e32 v28, v46, v28
	v_pk_mul_f32 v[30:31], v[18:19], v[18:19]
	v_add_f32_e32 v28, v28, v29
	v_add_f32_e32 v28, v28, v30
	v_pk_mul_f32 v[90:91], v[20:21], v[20:21]
	v_add_f32_e32 v28, v28, v31
	v_add_f32_e32 v28, v28, v90
	v_pk_mul_f32 v[94:95], v[16:17], v[16:17]
	v_add_f32_e32 v28, v28, v91
	v_add_f32_e32 v28, v28, v94
	v_pk_mul_f32 v[76:77], v[6:7], v[6:7]
	v_add_f32_e32 v28, v28, v95
	v_add_f32_e32 v28, v28, v76
	v_pk_mul_f32 v[84:85], v[2:3], v[2:3]
	v_add_f32_e32 v28, v28, v77
	v_add_f32_e32 v28, v28, v84
	v_pk_mul_f32 v[8:9], v[4:5], v[4:5]
	v_add_f32_e32 v28, v28, v85
	v_add_f32_e32 v8, v28, v8
	v_pk_mul_f32 v[10:11], v[0:1], v[0:1]
	v_add_f32_e32 v8, v8, v9
	v_add_f32_e32 v8, v8, v10
	v_pk_mul_f32 v[72:73], v[64:65], v[64:65]
	v_add_f32_e32 v8, v8, v11
	v_add_f32_e32 v8, v8, v72
	v_pk_mul_f32 v[88:89], v[68:69], v[68:69]
	v_add_f32_e32 v8, v8, v73
	v_add_f32_e32 v8, v8, v88
	v_add_f32_e32 v8, v8, v89
	global_load_dwordx4 v[102:105], v[184:185], off offset:320
	global_load_dwordx4 v[106:109], v[184:185], off offset:352
	global_load_dwordx4 v[110:113], v[184:185], off offset:384
	global_load_dwordx4 v[114:117], v[184:185], off offset:416
	global_load_dwordx4 v[118:121], v[184:185], off offset:448
	global_load_dwordx4 v[122:125], v[184:185], off offset:480
	ds_bpermute_b32 v9, v173, v8
	s_waitcnt lgkmcnt(0)
	v_add_f32_e32 v8, v8, v9
	v_fmamk_f32 v8, v8, 0x3c000000, v216
	v_cmp_gt_f32_e32 vcc, s29, v8
	v_mul_f32_e32 v9, 0x4b800000, v8
	s_nop 0
	v_cndmask_b32_e32 v8, v8, v9, vcc
	v_rsq_f32_e32 v8, v8
	s_nop 0
	v_mul_f32_e32 v9, 0x45800000, v8
	v_cndmask_b32_e32 v8, v8, v9, vcc
	v_mul_f32_e32 v8, v171, v8
	v_pk_mul_f32 v[10:11], v[92:93], v[8:9] op_sel_hi:[1,0]
	v_pk_mul_f32 v[12:13], v[82:83], v[8:9] op_sel_hi:[1,0]
	s_waitcnt vmcnt(15)
	v_pk_mul_f32 v[10:11], v[148:149], v[10:11]
	v_pk_mul_f32 v[12:13], v[150:151], v[12:13]
	v_cvt_pk_bf16_f32 v10, v10, v11
	v_cvt_pk_bf16_f32 v11, v12, v13
	global_store_dwordx2 v[66:67], v[10:11], off
	v_pk_mul_f32 v[70:71], v[96:97], v[8:9] op_sel_hi:[1,0]
	v_pk_mul_f32 v[72:73], v[86:87], v[8:9] op_sel_hi:[1,0]
	s_waitcnt vmcnt(15)
	v_pk_mul_f32 v[70:71], v[152:153], v[70:71]
	v_pk_mul_f32 v[72:73], v[154:155], v[72:73]
	v_cvt_pk_bf16_f32 v70, v70, v71
	v_cvt_pk_bf16_f32 v71, v72, v73
	global_store_dwordx2 v[66:67], v[70:71], off offset:16
	v_pk_mul_f32 v[10:11], v[100:101], v[8:9] op_sel_hi:[1,0]
	v_pk_mul_f32 v[12:13], v[78:79], v[8:9] op_sel_hi:[1,0]
	s_waitcnt vmcnt(15)
	v_pk_mul_f32 v[10:11], v[156:157], v[10:11]
	v_pk_mul_f32 v[12:13], v[158:159], v[12:13]
	v_cvt_pk_bf16_f32 v10, v10, v11
	v_cvt_pk_bf16_f32 v11, v12, v13
	global_store_dwordx2 v[66:67], v[10:11], off offset:32
	v_pk_mul_f32 v[70:71], v[60:61], v[8:9] op_sel_hi:[1,0]
	v_pk_mul_f32 v[72:73], v[56:57], v[8:9] op_sel_hi:[1,0]
	s_waitcnt vmcnt(15)
	v_pk_mul_f32 v[70:71], v[162:163], v[70:71]
	v_pk_mul_f32 v[72:73], v[164:165], v[72:73]
	v_cvt_pk_bf16_f32 v70, v70, v71
	v_cvt_pk_bf16_f32 v71, v72, v73
	global_store_dwordx2 v[66:67], v[70:71], off offset:48
	v_pk_mul_f32 v[10:11], v[58:59], v[8:9] op_sel_hi:[1,0]
	v_pk_mul_f32 v[12:13], v[52:53], v[8:9] op_sel_hi:[1,0]
	s_waitcnt vmcnt(15)
	v_pk_mul_f32 v[10:11], v[222:223], v[10:11]
	v_pk_mul_f32 v[12:13], v[224:225], v[12:13]
	v_cvt_pk_bf16_f32 v10, v10, v11
	v_cvt_pk_bf16_f32 v11, v12, v13
	global_store_dwordx2 v[66:67], v[10:11], off offset:64
	v_pk_mul_f32 v[70:71], v[54:55], v[8:9] op_sel_hi:[1,0]
	v_pk_mul_f32 v[72:73], v[48:49], v[8:9] op_sel_hi:[1,0]
	s_waitcnt vmcnt(15)
	v_pk_mul_f32 v[70:71], v[236:237], v[70:71]
	v_pk_mul_f32 v[72:73], v[238:239], v[72:73]
	v_cvt_pk_bf16_f32 v70, v70, v71
	v_cvt_pk_bf16_f32 v71, v72, v73
	global_store_dwordx2 v[66:67], v[70:71], off offset:80
	v_pk_mul_f32 v[10:11], v[50:51], v[8:9] op_sel_hi:[1,0]
	v_pk_mul_f32 v[12:13], v[42:43], v[8:9] op_sel_hi:[1,0]
	s_waitcnt vmcnt(15)
	v_pk_mul_f32 v[10:11], v[240:241], v[10:11]
	v_pk_mul_f32 v[12:13], v[242:243], v[12:13]
	v_cvt_pk_bf16_f32 v10, v10, v11
	v_cvt_pk_bf16_f32 v11, v12, v13
	global_store_dwordx2 v[66:67], v[10:11], off offset:96
	v_pk_mul_f32 v[70:71], v[44:45], v[8:9] op_sel_hi:[1,0]
	v_pk_mul_f32 v[72:73], v[38:39], v[8:9] op_sel_hi:[1,0]
	s_waitcnt vmcnt(15)
	v_pk_mul_f32 v[70:71], v[244:245], v[70:71]
	v_pk_mul_f32 v[72:73], v[246:247], v[72:73]
	v_cvt_pk_bf16_f32 v70, v70, v71
	v_cvt_pk_bf16_f32 v71, v72, v73
	global_store_dwordx2 v[66:67], v[70:71], off offset:112
	v_pk_mul_f32 v[10:11], v[40:41], v[8:9] op_sel_hi:[1,0]
	v_pk_mul_f32 v[12:13], v[34:35], v[8:9] op_sel_hi:[1,0]
	s_waitcnt vmcnt(15)
	v_pk_mul_f32 v[10:11], v[248:249], v[10:11]
	v_pk_mul_f32 v[12:13], v[250:251], v[12:13]
	v_cvt_pk_bf16_f32 v10, v10, v11
	v_cvt_pk_bf16_f32 v11, v12, v13
	global_store_dwordx2 v[66:67], v[10:11], off offset:128
	v_pk_mul_f32 v[70:71], v[36:37], v[8:9] op_sel_hi:[1,0]
	v_pk_mul_f32 v[72:73], v[32:33], v[8:9] op_sel_hi:[1,0]
	s_waitcnt vmcnt(15)
	v_pk_mul_f32 v[70:71], v[230:231], v[70:71]
	v_pk_mul_f32 v[72:73], v[232:233], v[72:73]
	v_cvt_pk_bf16_f32 v70, v70, v71
	v_cvt_pk_bf16_f32 v71, v72, v73
	global_store_dwordx2 v[66:67], v[70:71], off offset:144
	v_pk_mul_f32 v[10:11], v[26:27], v[8:9] op_sel_hi:[1,0]
	v_pk_mul_f32 v[12:13], v[22:23], v[8:9] op_sel_hi:[1,0]
	s_waitcnt vmcnt(15)
	v_pk_mul_f32 v[10:11], v[102:103], v[10:11]
	v_pk_mul_f32 v[12:13], v[104:105], v[12:13]
	v_cvt_pk_bf16_f32 v10, v10, v11
	v_cvt_pk_bf16_f32 v11, v12, v13
	global_store_dwordx2 v[66:67], v[10:11], off offset:160
	v_pk_mul_f32 v[70:71], v[24:25], v[8:9] op_sel_hi:[1,0]
	v_pk_mul_f32 v[72:73], v[18:19], v[8:9] op_sel_hi:[1,0]
	s_waitcnt vmcnt(15)
	v_pk_mul_f32 v[70:71], v[106:107], v[70:71]
	v_pk_mul_f32 v[72:73], v[108:109], v[72:73]
	v_cvt_pk_bf16_f32 v70, v70, v71
	v_cvt_pk_bf16_f32 v71, v72, v73
	global_store_dwordx2 v[66:67], v[70:71], off offset:176
	v_pk_mul_f32 v[10:11], v[20:21], v[8:9] op_sel_hi:[1,0]
	v_pk_mul_f32 v[12:13], v[16:17], v[8:9] op_sel_hi:[1,0]
	s_waitcnt vmcnt(15)
	v_pk_mul_f32 v[10:11], v[110:111], v[10:11]
	v_pk_mul_f32 v[12:13], v[112:113], v[12:13]
	v_cvt_pk_bf16_f32 v10, v10, v11
	v_cvt_pk_bf16_f32 v11, v12, v13
	global_store_dwordx2 v[66:67], v[10:11], off offset:192
	v_pk_mul_f32 v[70:71], v[6:7], v[8:9] op_sel_hi:[1,0]
	v_pk_mul_f32 v[72:73], v[2:3], v[8:9] op_sel_hi:[1,0]
	s_waitcnt vmcnt(15)
	v_pk_mul_f32 v[70:71], v[114:115], v[70:71]
	v_pk_mul_f32 v[72:73], v[116:117], v[72:73]
	v_cvt_pk_bf16_f32 v70, v70, v71
	v_cvt_pk_bf16_f32 v71, v72, v73
	global_store_dwordx2 v[66:67], v[70:71], off offset:208
	v_pk_mul_f32 v[10:11], v[4:5], v[8:9] op_sel_hi:[1,0]
	v_pk_mul_f32 v[12:13], v[0:1], v[8:9] op_sel_hi:[1,0]
	s_waitcnt vmcnt(15)
	v_pk_mul_f32 v[10:11], v[118:119], v[10:11]
	v_pk_mul_f32 v[12:13], v[120:121], v[12:13]
	v_cvt_pk_bf16_f32 v10, v10, v11
	v_cvt_pk_bf16_f32 v11, v12, v13
	global_store_dwordx2 v[66:67], v[10:11], off offset:224
	v_pk_mul_f32 v[70:71], v[64:65], v[8:9] op_sel_hi:[1,0]
	v_pk_mul_f32 v[72:73], v[68:69], v[8:9] op_sel_hi:[1,0]
	s_waitcnt vmcnt(15)
	v_pk_mul_f32 v[70:71], v[122:123], v[70:71]
	v_pk_mul_f32 v[72:73], v[124:125], v[72:73]
	v_cvt_pk_bf16_f32 v70, v70, v71
	v_cvt_pk_bf16_f32 v71, v72, v73
	global_store_dwordx2 v[66:67], v[70:71], off offset:240
	s_branch .LBB0_195
